# P4 epilogue: per-row RMS scale computed once per row per tile (loads issued at tile start, shared via 1KB LDS) instead of 32 redundant SSQ loads + 8 reductions per wave; store drain overlapped with fi
# speedup vs baseline: 1.0298x; 1.0298x over previous
; #define PG8_STAGE(bufoff, gbase, voff) do { _Pragma("unroll") for (int _i = 0; _i < 2; ++_i) \
;         __builtin_amdgcn_global_load_lds((const unsigned*)((const char*)(gbase) + (voff)[_i]), (PG8_LAS unsigned*)(lds + (bufoff) + ldsw + _i * 8192), 16, 0, 0); } while (0)
; #define PG8_WAIT_V(n) asm volatile("s_waitcnt vmcnt(" #n ")" ::: "memory")
; #define PG8_BAR __builtin_amdgcn_s_barrier()
; template <class Epi, class Sched, bool ALIGN_EPI = false, bool SP2 = false>
; __device__ __forceinline__ void gemm_phase(PG8_LAS unsigned char* lds, const Gemm g, const Sched& S, const Epi& E) {
;     ...
;     for (int i = 0; i < 2; ++i) { int R, C; stage_rc(tid * 16 + i * 8192, R, C); const int Rb = Epi::PERM ? ((R & ~31) + perm32(R & 31)) : R;
;         voffA[i] = (unsigned)(R * K + C) * 2u; voffB[i] = (unsigned)(Rb * K + C) * 2u; }
;     const size_t kstep = (size_t)(BK * 2);
;     const size_t hstep = (size_t)HALF * K * 2;
;     const size_t tstep = 2 * hstep;
;     const unsigned ldsw = (unsigned)wid * 1024u;
;     const int aoff = lds_byte(wr * 64 + fr, fq * 8), boff = lds_byte(wc * 32 + fr, fq * 8);
;     ...
;     Unit cur, nxt; int ui = 0;
;     if (!S.next(0, cur)) return;
;     f32x4 acc[2][2][4][2];
; #pragma unroll
;     for (int a = 0; a < 2; ++a)
; #pragma unroll
;         for (int b = 0; b < 2; ++b)
; #pragma unroll
;             for (int m = 0; m < 4; ++m)
; #pragma unroll
;                 for (int n = 0; n < 2; ++n) acc[a][b][m][n] = (f32x4){0.f, 0.f, 0.f, 0.f};
;     bf16x8 At[4][2], B0[2][2], B1[2][2];
;     const char* cA = (const char*)g.A + (size_t)cur.pm * tstep; const char* cB = (const char*)g.Bt + (size_t)cur.pn * tstep;
;     S.a_ready(cur);
;     if constexpr (SP2) {
;         PG8_STAGE(PG8_SB(0, 0), cB, voffB); PG8_STAGE(PG8_SB(0, 1), cB + hstep, voffB); PG8_STAGE(PG8_SA(0, 0), cA, voffA); PG8_STAGE(PG8_SA(0, 1), cA + hstep, voffA);
;         if (wr == 1) PG8_BAR;
;         PG8_WAIT_V(2); PG8_BAR;
;         PG8_STAGE(PG8_SB(1, 0), cB + kstep, voffB); PG8_STAGE(PG8_SA(1, 0), cA + kstep, voffA); PG8_STAGE(PG8_SB(1, 1), cB + hstep + kstep, voffB);
;         PG8_WAIT_V(6); PG8_BAR;
.LBB0_854:
	s_lshl_b32 s12, s12, 5
	s_and_b32 s17, s12, 0x60
	s_mov_b64 s[12:13], 0x80
	s_add_i32 m0, s38, 0x18000
	v_lshl_add_u64 v[6:7], v[6:7], 0, s[12:13]
	s_lshl_b32 s16, s8, 13
	s_lshl_b32 s18, s17, 7
	s_waitcnt vmcnt(2)
	s_barrier
	global_load_lds_dwordx4 v[6:7], off
	v_lshl_add_u64 v[4:5], v[4:5], 0, s[12:13]
	s_add_i32 m0, s38, 0x1a000
	s_add_i32 s42, s38, 0x8000
	s_add_i32 s43, s38, 0xa000
	global_load_lds_dwordx4 v[4:5], off
	v_lshl_add_u64 v[0:1], v[0:1], 0, s[12:13]
	s_mov_b32 m0, s42
	s_add_u32 s14, s28, 0x40080
	global_load_lds_dwordx4 v[0:1], off
	v_lshl_add_u64 v[0:1], v[2:3], 0, s[12:13]
	s_mov_b32 m0, s43
	s_addc_u32 s15, s29, 0
	global_load_lds_dwordx4 v[0:1], off
	s_add_i32 m0, s38, 0x1c000
	v_lshl_add_u64 v[0:1], s[14:15], 0, v[132:133]
	global_load_lds_dwordx4 v[0:1], off
	v_lshl_add_u64 v[0:1], s[14:15], 0, v[128:129]
	s_add_i32 m0, s38, 0x1e000
	s_cmpk_lt_u32 s7, 0x100
	global_load_lds_dwordx4 v[0:1], off
	v_lshrrev_b32_e32 v0, 1, v10
	v_and_b32_e32 v0, 24, v0
	v_and_b32_e32 v1, 15, v10
	v_lshlrev_b32_e32 v2, 1, v0
	v_lshl_or_b32 v150, s8, 6, v1
	v_lshl_or_b32 v1, v1, 6, v2
	v_lshlrev_b32_e32 v2, 2, v10
	v_and_b32_e32 v2, 32, v2
	v_bitop3_b32 v3, v1, s16, v2 bitop3:0xde
	v_bitop3_b32 v151, v1, s18, v2 bitop3:0xde
	v_lshlrev_b32_e32 v1, 14, v13
	v_and_b32_e32 v1, 0xffff8000, v1
	v_lshl_add_u32 v1, v12, 11, v1
	v_and_b32_e32 v2, 1, v13
	v_lshl_or_b32 v1, v2, 6, v1
	v_lshl_add_u32 v138, v14, 1, v1
	v_lshlrev_b32_e32 v1, 14, v8
	v_and_b32_e32 v1, 0xffff8000, v1
	s_waitcnt vmcnt(6)
	v_lshl_add_u32 v1, v9, 11, v1
	v_and_b32_e32 v2, 1, v8
	s_cselect_b64 s[14:15], -1, 0
	v_lshl_or_b32 v1, v2, 6, v1
	s_add_i32 s45, 0, 0x10000
	s_add_i32 s46, 0, 0x14000
	s_sext_i32_i16 s25, s6
	s_ashr_i32 s44, s3, 31
	v_mov_b32_e32 v139, v137
	v_lshl_add_u32 v140, v11, 1, v1
	v_mov_b32_e32 v141, v137
	v_mov_b64_e32 v[142:143], 0x1658
	v_mov_b64_e32 v[144:145], 0x1657
	v_add_u32_e32 v152, s45, v151
	v_add_u32_e32 v153, s46, v151
	v_add_u32_e32 v154, 0, v3
	v_mov_b32_e32 v155, 0x358637bd
	s_mov_b32 s47, 0x800000
	s_movk_i32 s48, 0x1600
	s_lshl_b32 s8, s17, 1
	v_lshlrev_b32_e32 v136, 1, v0
	s_mov_b32 s49, s9
	v_and_b32_e32 v246, 0xff, v182
	v_lshlrev_b32_e32 v247, 2, v246
	v_add_u32_e32 v247, 0x20000, v247
	v_lshlrev_b32_e32 v246, 6, v246
	s_waitcnt vmcnt(0)
	s_barrier
	s_branch .LBB0_857

; #define PG8_STAGE(bufoff, gbase, voff) do { _Pragma("unroll") for (int _i = 0; _i < 2; ++_i) \
;         __builtin_amdgcn_global_load_lds((const unsigned*)((const char*)(gbase) + (voff)[_i]), (PG8_LAS unsigned*)(lds + (bufoff) + ldsw + _i * 8192), 16, 0, 0); } while (0)
; #define PG8_LDA(dst, b, h) do { _Pragma("unroll") for (int m = 0; m < 4; ++m) _Pragma("unroll") for (int k = 0; k < 2; ++k) dst[m][k] = *(const PG8_LAS bf16x8*)(lds + PG8_SA(b, h) + aoff + m * 2048 + k * 1024); } while (0)
; #define PG8_LDB(dst, b, h) do { _Pragma("unroll") for (int n = 0; n < 2; ++n) _Pragma("unroll") for (int k = 0; k < 2; ++k) dst[n][k] = *(const PG8_LAS bf16x8*)(lds + PG8_SB(b, h) + boff + n * 2048 + k * 1024); } while (0)
; #define PG8_MMA(ai, bj, At, Bt) do { __builtin_amdgcn_s_setprio(1); _Pragma("unroll") for (int m = 0; m < 4; ++m) _Pragma("unroll") for (int n = 0; n < 2; ++n) _Pragma("unroll") for (int k = 0; k < 2; ++k) \
;         acc[ai][bj][m][n] = __builtin_amdgcn_mfma_f32_16x16x32_bf16(Bt[n][k], At[m][k], acc[ai][bj][m][n], 0, 0, 0); __builtin_amdgcn_s_setprio(0); } while (0)
; #define PG8_WAIT_V(n) asm volatile("s_waitcnt vmcnt(" #n ")" ::: "memory")
; #define PG8_WAIT_L(n) asm volatile("s_waitcnt lgkmcnt(" #n ")" ::: "memory")
; #define PG8_BAR __builtin_amdgcn_s_barrier()
; #define PG8_SCHED __builtin_amdgcn_sched_barrier(0)
; template <class Epi, class Sched, bool ALIGN_EPI = false, bool SP2 = false>
; __device__ __forceinline__ void gemm_phase(PG8_LAS unsigned char* lds, const Gemm g, const Sched& S, const Epi& E) {
;     ...
;             PG8_LDB(B0, 0, 0); PG8_LDB(B1, 0, 1); PG8_SCHED; PG8_LDA(At, 0, 0); PG8_STAGE(PG8_SA(1, 1), a1 + hstep, voffA);
;             PG8_WAIT_V(8); PG8_WAIT_L(0); PG8_BAR; PG8_MMA(0, 0, At, B0); PG8_MMA(0, 1, At, B1); PG8_BAR; PG8_SCHED;
;             PG8_LDA(At, 0, 1); PG8_STAGE(PG8_SB(0, 0), b2, voffB); PG8_STAGE(PG8_SB(0, 1), b2 + hstep, voffB); PG8_STAGE(PG8_SA(0, 0), a2, voffA);
;     DI void operator()(const f32x4 (&acc)[2][2][4][2], const Unit& u, int wr, int wc, int fr, int fq) const {
;     ...
;                 const float* sp = SSQ + (size_t)row * 16;
;                 const f32x4 s0 = *(const f32x4*)sp, s1 = *(const f32x4*)(sp + 4), s2 = *(const f32x4*)(sp + 8), s3 = *(const f32x4*)(sp + 12);
.LBB0_859:
	s_ashr_i32 s19, s18, 31
	s_lshl_b64 s[20:21], s[18:19], 19
	s_add_u32 s20, s50, s20
	s_addc_u32 s21, s51, s21
	s_and_b64 s[22:23], s[6:7], exec
	s_cselect_b32 s19, s21, s27
	s_cselect_b32 s54, s20, s26
	s_ashr_i32 s17, s16, 31
	s_lshl_b64 s[22:23], s[16:17], 19
	s_add_u32 s22, s33, s22
	s_addc_u32 s23, s34, s23
	s_and_b64 s[30:31], s[6:7], exec
	s_cselect_b32 s17, s23, s29
	s_cselect_b32 s55, s22, s28
	s_add_u32 s26, s26, 0x40080
	s_addc_u32 s27, s27, 0
	s_add_u32 s56, s28, 0x100
	s_addc_u32 s57, s29, 0
	s_mov_b32 s58, -2
	s_lshl_b32 s59, s24, 14
	v_add_u32_e32 v248, s59, v246
	global_load_dwordx4 v[230:233], v248, s[0:1]
	global_load_dwordx4 v[234:237], v248, s[0:1] offset:16
	global_load_dwordx4 v[238:241], v248, s[0:1] offset:32
	global_load_dwordx4 v[242:245], v248, s[0:1] offset:48
	ds_read_b128 v[146:149], v152
	ds_read_b128 v[156:159], v152 offset:1024
	ds_read_b128 v[160:163], v152 offset:2048
	ds_read_b128 v[164:167], v152 offset:3072
	ds_read_b128 v[168:171], v153
	ds_read_b128 v[172:175], v153 offset:1024
	ds_read_b128 v[176:179], v153 offset:2048
	ds_read_b128 v[186:189], v153 offset:3072
	s_add_u32 s28, s26, 0xfffc0080
	s_addc_u32 s29, s27, -1
	s_cmp_eq_u32 s58, 12
	s_cselect_b32 s31, s19, s29
	s_cselect_b32 s30, s54, s28
	s_cselect_b32 s29, s17, s57
	s_cselect_b32 s28, s55, s56
	v_lshl_add_u64 v[180:181], s[26:27], 0, v[138:139]
	s_add_i32 m0, s38, 0xc000
	ds_read_b128 v[190:193], v154
	ds_read_b128 v[194:197], v154 offset:1024
	ds_read_b128 v[198:201], v154 offset:2048
	ds_read_b128 v[202:205], v154 offset:3072
	ds_read_b128 v[206:209], v154 offset:4096
	ds_read_b128 v[210:213], v154 offset:5120
	ds_read_b128 v[214:217], v154 offset:6144
	ds_read_b128 v[218:221], v154 offset:7168
	global_load_lds_dwordx4 v[180:181], off
	v_lshl_add_u64 v[180:181], s[26:27], 0, v[140:141]
	s_add_i32 m0, s38, 0xe000
	s_nop 0
	global_load_lds_dwordx4 v[180:181], off
	s_waitcnt vmcnt(20)
	s_waitcnt lgkmcnt(0)
	s_barrier
	s_setprio 1
	s_waitcnt lgkmcnt(0)
	v_mfma_f32_16x16x32_bf16 v[124:127], v[146:149], v[190:193], 0
	v_mfma_f32_16x16x32_bf16 v[120:123], v[160:163], v[190:193], 0
	v_mfma_f32_16x16x32_bf16 v[108:111], v[146:149], v[198:201], 0
	v_mfma_f32_16x16x32_bf16 v[104:107], v[160:163], v[198:201], 0
	v_mfma_f32_16x16x32_bf16 v[92:95], v[146:149], v[206:209], 0
	v_mfma_f32_16x16x32_bf16 v[88:91], v[160:163], v[206:209], 0
	v_mfma_f32_16x16x32_bf16 v[76:79], v[146:149], v[214:217], 0
	v_mfma_f32_16x16x32_bf16 v[72:75], v[160:163], v[214:217], 0
	v_mfma_f32_16x16x32_bf16 v[124:127], v[156:159], v[194:197], v[124:127]
	v_mfma_f32_16x16x32_bf16 v[120:123], v[164:167], v[194:197], v[120:123]
	v_mfma_f32_16x16x32_bf16 v[108:111], v[156:159], v[202:205], v[108:111]
	v_mfma_f32_16x16x32_bf16 v[104:107], v[164:167], v[202:205], v[104:107]
	v_mfma_f32_16x16x32_bf16 v[92:95], v[156:159], v[210:213], v[92:95]
	v_mfma_f32_16x16x32_bf16 v[88:91], v[164:167], v[210:213], v[88:91]
	v_mfma_f32_16x16x32_bf16 v[76:79], v[156:159], v[218:221], v[76:79]
	v_mfma_f32_16x16x32_bf16 v[72:75], v[164:167], v[218:221], v[72:75]
	s_setprio 0
	s_setprio 1
	v_mfma_f32_16x16x32_bf16 v[116:119], v[168:171], v[190:193], 0
	v_mfma_f32_16x16x32_bf16 v[112:115], v[176:179], v[190:193], 0
	v_mfma_f32_16x16x32_bf16 v[100:103], v[168:171], v[198:201], 0
	v_mfma_f32_16x16x32_bf16 v[96:99], v[176:179], v[198:201], 0
	v_mfma_f32_16x16x32_bf16 v[84:87], v[168:171], v[206:209], 0
	v_mfma_f32_16x16x32_bf16 v[80:83], v[176:179], v[206:209], 0
	v_mfma_f32_16x16x32_bf16 v[68:71], v[168:171], v[214:217], 0
	v_mfma_f32_16x16x32_bf16 v[64:67], v[176:179], v[214:217], 0
	v_mfma_f32_16x16x32_bf16 v[116:119], v[172:175], v[194:197], v[116:119]
	v_mfma_f32_16x16x32_bf16 v[112:115], v[186:189], v[194:197], v[112:115]
	v_mfma_f32_16x16x32_bf16 v[100:103], v[172:175], v[202:205], v[100:103]
	v_mfma_f32_16x16x32_bf16 v[96:99], v[186:189], v[202:205], v[96:99]
	v_mfma_f32_16x16x32_bf16 v[84:87], v[172:175], v[210:213], v[84:87]
	v_mfma_f32_16x16x32_bf16 v[80:83], v[186:189], v[210:213], v[80:83]
	v_mfma_f32_16x16x32_bf16 v[68:71], v[172:175], v[218:221], v[68:71]
	v_mfma_f32_16x16x32_bf16 v[64:67], v[186:189], v[218:221], v[64:67]
	s_setprio 0
	s_barrier
	s_add_i32 s59, s45, s35
	v_lshl_add_u64 v[180:181], s[28:29], 0, v[132:133]
	s_mov_b32 m0, s59
	ds_read_b128 v[190:193], v154 offset:16384
	ds_read_b128 v[194:197], v154 offset:17408
	ds_read_b128 v[198:201], v154 offset:18432
	ds_read_b128 v[202:205], v154 offset:19456
	ds_read_b128 v[206:209], v154 offset:20480
	ds_read_b128 v[210:213], v154 offset:21504
	ds_read_b128 v[214:217], v154 offset:22528
	ds_read_b128 v[218:221], v154 offset:23552
	global_load_lds_dwordx4 v[180:181], off
	s_add_i32 m0, s59, 0x2000
	s_add_u32 s60, s28, 0x40000
	v_lshl_add_u64 v[222:223], s[28:29], 0, v[128:129]
	s_addc_u32 s61, s29, 0
	s_add_i32 s59, s46, s35
	global_load_lds_dwordx4 v[222:223], off
	v_lshl_add_u64 v[224:225], s[60:61], 0, v[132:133]
	s_mov_b32 m0, s59
	v_lshl_add_u64 v[226:227], s[30:31], 0, v[130:131]
	global_load_lds_dwordx4 v[224:225], off
	v_lshl_add_u64 v[224:225], s[60:61], 0, v[128:129]
	s_add_i32 m0, s59, 0x2000
	s_nop 0
	global_load_lds_dwordx4 v[224:225], off
	v_lshl_add_u64 v[224:225], s[30:31], 0, v[134:135]
	s_mov_b32 m0, s38
	s_nop 0
	global_load_lds_dwordx4 v[224:225], off
	s_mov_b32 m0, s39
	s_nop 0
	global_load_lds_dwordx4 v[226:227], off
	s_waitcnt vmcnt(20)
	s_waitcnt lgkmcnt(0)
	s_barrier
; #define PG8_STAGE(bufoff, gbase, voff) do { _Pragma("unroll") for (int _i = 0; _i < 2; ++_i) \
;         __builtin_amdgcn_global_load_lds((const unsigned*)((const char*)(gbase) + (voff)[_i]), (PG8_LAS unsigned*)(lds + (bufoff) + ldsw + _i * 8192), 16, 0, 0); } while (0)
; #define PG8_LDA(dst, b, h) do { _Pragma("unroll") for (int m = 0; m < 4; ++m) _Pragma("unroll") for (int k = 0; k < 2; ++k) dst[m][k] = *(const PG8_LAS bf16x8*)(lds + PG8_SA(b, h) + aoff + m * 2048 + k * 1024); } while (0)
; #define PG8_LDB(dst, b, h) do { _Pragma("unroll") for (int n = 0; n < 2; ++n) _Pragma("unroll") for (int k = 0; k < 2; ++k) dst[n][k] = *(const PG8_LAS bf16x8*)(lds + PG8_SB(b, h) + boff + n * 2048 + k * 1024); } while (0)
; #define PG8_MMA(ai, bj, At, Bt) do { __builtin_amdgcn_s_setprio(1); _Pragma("unroll") for (int m = 0; m < 4; ++m) _Pragma("unroll") for (int n = 0; n < 2; ++n) _Pragma("unroll") for (int k = 0; k < 2; ++k) \
;         acc[ai][bj][m][n] = __builtin_amdgcn_mfma_f32_16x16x32_bf16(Bt[n][k], At[m][k], acc[ai][bj][m][n], 0, 0, 0); __builtin_amdgcn_s_setprio(0); } while (0)
; #define PG8_WAIT_V(n) asm volatile("s_waitcnt vmcnt(" #n ")" ::: "memory")
; #define PG8_WAIT_L(n) asm volatile("s_waitcnt lgkmcnt(" #n ")" ::: "memory")
; #define PG8_BAR __builtin_amdgcn_s_barrier()
; #define PG8_SCHED __builtin_amdgcn_sched_barrier(0)
; template <class Epi, class Sched, bool ALIGN_EPI = false, bool SP2 = false>
; __device__ __forceinline__ void gemm_phase(PG8_LAS unsigned char* lds, const Gemm g, const Sched& S, const Epi& E) {
;     ...
;             PG8_WAIT_V(8); PG8_WAIT_L(0); PG8_BAR; PG8_MMA(1, 0, At, B0); PG8_MMA(1, 1, At, B1); PG8_BAR; PG8_SCHED;
;             PG8_LDB(B0, 1, 0); PG8_LDB(B1, 1, 1); PG8_SCHED; PG8_LDA(At, 1, 0); PG8_STAGE(PG8_SA(0, 1), a2 + hstep, voffA);
;             PG8_WAIT_V(8); PG8_WAIT_L(0); PG8_BAR; PG8_MMA(0, 0, At, B0); PG8_MMA(0, 1, At, B1); PG8_BAR; PG8_SCHED;
	s_setprio 1
	s_waitcnt lgkmcnt(0)
	v_mfma_f32_16x16x32_bf16 v[60:63], v[146:149], v[190:193], 0
	v_mfma_f32_16x16x32_bf16 v[56:59], v[160:163], v[190:193], 0
	v_mfma_f32_16x16x32_bf16 v[44:47], v[146:149], v[198:201], 0
	v_mfma_f32_16x16x32_bf16 v[40:43], v[160:163], v[198:201], 0
	v_mfma_f32_16x16x32_bf16 v[28:31], v[146:149], v[206:209], 0
	v_mfma_f32_16x16x32_bf16 v[24:27], v[160:163], v[206:209], 0
	v_mfma_f32_16x16x32_bf16 v[12:15], v[146:149], v[214:217], 0
	v_mfma_f32_16x16x32_bf16 v[8:11], v[160:163], v[214:217], 0
	v_mfma_f32_16x16x32_bf16 v[60:63], v[156:159], v[194:197], v[60:63]
	v_mfma_f32_16x16x32_bf16 v[56:59], v[164:167], v[194:197], v[56:59]
	v_mfma_f32_16x16x32_bf16 v[44:47], v[156:159], v[202:205], v[44:47]
	v_mfma_f32_16x16x32_bf16 v[40:43], v[164:167], v[202:205], v[40:43]
	v_mfma_f32_16x16x32_bf16 v[28:31], v[156:159], v[210:213], v[28:31]
	v_mfma_f32_16x16x32_bf16 v[24:27], v[164:167], v[210:213], v[24:27]
	v_mfma_f32_16x16x32_bf16 v[12:15], v[156:159], v[218:221], v[12:15]
	v_mfma_f32_16x16x32_bf16 v[8:11], v[164:167], v[218:221], v[8:11]
	s_setprio 0
	s_setprio 1
	v_mfma_f32_16x16x32_bf16 v[52:55], v[168:171], v[190:193], 0
	v_mfma_f32_16x16x32_bf16 v[48:51], v[176:179], v[190:193], 0
	v_mfma_f32_16x16x32_bf16 v[36:39], v[168:171], v[198:201], 0
	v_mfma_f32_16x16x32_bf16 v[32:35], v[176:179], v[198:201], 0
	v_mfma_f32_16x16x32_bf16 v[20:23], v[168:171], v[206:209], 0
	v_mfma_f32_16x16x32_bf16 v[16:19], v[176:179], v[206:209], 0
	v_mfma_f32_16x16x32_bf16 v[4:7], v[168:171], v[214:217], 0
	v_mfma_f32_16x16x32_bf16 v[0:3], v[176:179], v[214:217], 0
	v_mfma_f32_16x16x32_bf16 v[52:55], v[172:175], v[194:197], v[52:55]
	v_mfma_f32_16x16x32_bf16 v[48:51], v[186:189], v[194:197], v[48:51]
	v_mfma_f32_16x16x32_bf16 v[36:39], v[172:175], v[202:205], v[36:39]
	v_mfma_f32_16x16x32_bf16 v[32:35], v[186:189], v[202:205], v[32:35]
	v_mfma_f32_16x16x32_bf16 v[20:23], v[172:175], v[210:213], v[20:23]
	v_mfma_f32_16x16x32_bf16 v[16:19], v[186:189], v[210:213], v[16:19]
	v_mfma_f32_16x16x32_bf16 v[4:7], v[172:175], v[218:221], v[4:7]
	v_mfma_f32_16x16x32_bf16 v[0:3], v[186:189], v[218:221], v[0:3]
	s_setprio 0
	s_barrier
	s_add_i32 s59, 0, 0x18000
	s_add_i32 s60, 0, 0x1c000
	v_add_u32_e32 v164, s59, v151
	v_add_u32_e32 v185, s60, v151
	ds_read_b128 v[146:149], v164
	ds_read_b128 v[156:159], v164 offset:1024
	ds_read_b128 v[160:163], v164 offset:2048
	ds_read_b128 v[164:167], v164 offset:3072
	ds_read_b128 v[168:171], v185
	ds_read_b128 v[172:175], v185 offset:1024
	ds_read_b128 v[176:179], v185 offset:2048
	ds_read_b128 v[186:189], v185 offset:3072
	s_add_u32 s30, s30, 0x40000
	s_addc_u32 s31, s31, 0
	s_mov_b32 m0, s40
	v_lshl_add_u64 v[228:229], s[30:31], 0, v[134:135]
	ds_read_b128 v[190:193], v154 offset:32768
	ds_read_b128 v[194:197], v154 offset:33792
	ds_read_b128 v[198:201], v154 offset:34816
	ds_read_b128 v[202:205], v154 offset:35840
	ds_read_b128 v[206:209], v154 offset:36864
	ds_read_b128 v[210:213], v154 offset:37888
	ds_read_b128 v[214:217], v154 offset:38912
	ds_read_b128 v[218:221], v154 offset:39936
	global_load_lds_dwordx4 v[228:229], off
	v_lshl_add_u64 v[228:229], s[30:31], 0, v[130:131]
	s_mov_b32 m0, s41
	s_nop 0
	global_load_lds_dwordx4 v[228:229], off
	s_waitcnt vmcnt(8)
	s_waitcnt lgkmcnt(0)
	s_barrier
	s_setprio 1
	s_waitcnt lgkmcnt(0)
	v_mfma_f32_16x16x32_bf16 v[124:127], v[146:149], v[190:193], v[124:127]
	v_mfma_f32_16x16x32_bf16 v[120:123], v[160:163], v[190:193], v[120:123]
	v_mfma_f32_16x16x32_bf16 v[108:111], v[146:149], v[198:201], v[108:111]
	v_mfma_f32_16x16x32_bf16 v[104:107], v[160:163], v[198:201], v[104:107]
	v_mfma_f32_16x16x32_bf16 v[92:95], v[146:149], v[206:209], v[92:95]
	v_mfma_f32_16x16x32_bf16 v[88:91], v[160:163], v[206:209], v[88:91]
	v_mfma_f32_16x16x32_bf16 v[76:79], v[146:149], v[214:217], v[76:79]
	v_mfma_f32_16x16x32_bf16 v[72:75], v[160:163], v[214:217], v[72:75]
	v_mfma_f32_16x16x32_bf16 v[124:127], v[156:159], v[194:197], v[124:127]
	v_mfma_f32_16x16x32_bf16 v[120:123], v[164:167], v[194:197], v[120:123]
	v_mfma_f32_16x16x32_bf16 v[108:111], v[156:159], v[202:205], v[108:111]
	v_mfma_f32_16x16x32_bf16 v[104:107], v[164:167], v[202:205], v[104:107]
	v_mfma_f32_16x16x32_bf16 v[92:95], v[156:159], v[210:213], v[92:95]
	v_mfma_f32_16x16x32_bf16 v[88:91], v[164:167], v[210:213], v[88:91]
	v_mfma_f32_16x16x32_bf16 v[76:79], v[156:159], v[218:221], v[76:79]
	v_mfma_f32_16x16x32_bf16 v[72:75], v[164:167], v[218:221], v[72:75]
	s_setprio 0
	s_setprio 1
	v_mfma_f32_16x16x32_bf16 v[116:119], v[168:171], v[190:193], v[116:119]
	v_mfma_f32_16x16x32_bf16 v[112:115], v[176:179], v[190:193], v[112:115]
	v_mfma_f32_16x16x32_bf16 v[100:103], v[168:171], v[198:201], v[100:103]
	v_mfma_f32_16x16x32_bf16 v[96:99], v[176:179], v[198:201], v[96:99]
	v_mfma_f32_16x16x32_bf16 v[84:87], v[168:171], v[206:209], v[84:87]
	v_mfma_f32_16x16x32_bf16 v[80:83], v[176:179], v[206:209], v[80:83]
	v_mfma_f32_16x16x32_bf16 v[68:71], v[168:171], v[214:217], v[68:71]
	v_mfma_f32_16x16x32_bf16 v[64:67], v[176:179], v[214:217], v[64:67]
	v_mfma_f32_16x16x32_bf16 v[116:119], v[172:175], v[194:197], v[116:119]
	v_mfma_f32_16x16x32_bf16 v[112:115], v[186:189], v[194:197], v[112:115]
	v_mfma_f32_16x16x32_bf16 v[100:103], v[172:175], v[202:205], v[100:103]
	v_mfma_f32_16x16x32_bf16 v[96:99], v[186:189], v[202:205], v[96:99]
	v_mfma_f32_16x16x32_bf16 v[84:87], v[172:175], v[210:213], v[84:87]
	v_mfma_f32_16x16x32_bf16 v[80:83], v[186:189], v[210:213], v[80:83]
	v_mfma_f32_16x16x32_bf16 v[68:71], v[172:175], v[218:221], v[68:71]
	v_mfma_f32_16x16x32_bf16 v[64:67], v[186:189], v[218:221], v[64:67]
	s_setprio 0
	s_barrier
; #define PG8_STAGE(bufoff, gbase, voff) do { _Pragma("unroll") for (int _i = 0; _i < 2; ++_i) \
;         __builtin_amdgcn_global_load_lds((const unsigned*)((const char*)(gbase) + (voff)[_i]), (PG8_LAS unsigned*)(lds + (bufoff) + ldsw + _i * 8192), 16, 0, 0); } while (0)
; #define PG8_LDA(dst, b, h) do { _Pragma("unroll") for (int m = 0; m < 4; ++m) _Pragma("unroll") for (int k = 0; k < 2; ++k) dst[m][k] = *(const PG8_LAS bf16x8*)(lds + PG8_SA(b, h) + aoff + m * 2048 + k * 1024); } while (0)
; #define PG8_MMA(ai, bj, At, Bt) do { __builtin_amdgcn_s_setprio(1); _Pragma("unroll") for (int m = 0; m < 4; ++m) _Pragma("unroll") for (int n = 0; n < 2; ++n) _Pragma("unroll") for (int k = 0; k < 2; ++k) \
;         acc[ai][bj][m][n] = __builtin_amdgcn_mfma_f32_16x16x32_bf16(Bt[n][k], At[m][k], acc[ai][bj][m][n], 0, 0, 0); __builtin_amdgcn_s_setprio(0); } while (0)
; #define PG8_WAIT_V(n) asm volatile("s_waitcnt vmcnt(" #n ")" ::: "memory")
; #define PG8_WAIT_L(n) asm volatile("s_waitcnt lgkmcnt(" #n ")" ::: "memory")
; #define PG8_BAR __builtin_amdgcn_s_barrier()
; #define PG8_SCHED __builtin_amdgcn_sched_barrier(0)
; template <class Epi, class Sched, bool ALIGN_EPI = false, bool SP2 = false>
; __device__ __forceinline__ void gemm_phase(PG8_LAS unsigned char* lds, const Gemm g, const Sched& S, const Epi& E) {
;     ...
;             PG8_LDA(At, 1, 1); PG8_STAGE(PG8_SB(1, 0), b3, voffB); PG8_STAGE(PG8_SB(1, 1), b3 + hstep, voffB); PG8_STAGE(PG8_SA(1, 0), a3, voffA);
;             PG8_WAIT_V(8); PG8_WAIT_L(0); PG8_BAR; PG8_MMA(1, 0, At, B0); PG8_MMA(1, 1, At, B1); PG8_BAR; PG8_SCHED;
	s_add_i32 s30, s59, s35
	v_lshl_add_u64 v[180:181], v[180:181], 0, s[12:13]
	s_mov_b32 m0, s30
	ds_read_b128 v[190:193], v154 offset:49152
	ds_read_b128 v[194:197], v154 offset:50176
	ds_read_b128 v[198:201], v154 offset:51200
	ds_read_b128 v[202:205], v154 offset:52224
	ds_read_b128 v[206:209], v154 offset:53248
	ds_read_b128 v[210:213], v154 offset:54272
	ds_read_b128 v[214:217], v154 offset:55296
	ds_read_b128 v[218:221], v154 offset:56320
	global_load_lds_dwordx4 v[180:181], off
	s_add_i32 m0, s30, 0x2000
	s_add_u32 s28, s28, 0x40080
	v_lshl_add_u64 v[180:181], v[222:223], 0, s[12:13]
	s_addc_u32 s29, s29, 0
	s_add_i32 s30, s60, s35
	global_load_lds_dwordx4 v[180:181], off
	v_lshl_add_u64 v[180:181], s[28:29], 0, v[132:133]
	s_mov_b32 m0, s30
	s_nop 0
	global_load_lds_dwordx4 v[180:181], off
	v_lshl_add_u64 v[180:181], s[28:29], 0, v[128:129]
	s_add_i32 m0, s30, 0x2000
	s_nop 0
	global_load_lds_dwordx4 v[180:181], off
	v_lshl_add_u64 v[180:181], v[224:225], 0, s[12:13]
	s_mov_b32 m0, s42
	s_nop 0
	global_load_lds_dwordx4 v[180:181], off
	v_lshl_add_u64 v[180:181], v[226:227], 0, s[12:13]
	s_mov_b32 m0, s43
	s_nop 0
	global_load_lds_dwordx4 v[180:181], off
	s_waitcnt vmcnt(8)
	s_waitcnt lgkmcnt(0)
	s_barrier
	s_setprio 1
	s_waitcnt lgkmcnt(0)
	v_mfma_f32_16x16x32_bf16 v[60:63], v[146:149], v[190:193], v[60:63]
	v_mfma_f32_16x16x32_bf16 v[56:59], v[160:163], v[190:193], v[56:59]
	v_mfma_f32_16x16x32_bf16 v[44:47], v[146:149], v[198:201], v[44:47]
	v_mfma_f32_16x16x32_bf16 v[40:43], v[160:163], v[198:201], v[40:43]
	v_mfma_f32_16x16x32_bf16 v[28:31], v[146:149], v[206:209], v[28:31]
	v_mfma_f32_16x16x32_bf16 v[24:27], v[160:163], v[206:209], v[24:27]
	v_mfma_f32_16x16x32_bf16 v[12:15], v[146:149], v[214:217], v[12:15]
	v_mfma_f32_16x16x32_bf16 v[8:11], v[160:163], v[214:217], v[8:11]
	v_mfma_f32_16x16x32_bf16 v[60:63], v[156:159], v[194:197], v[60:63]
	v_mfma_f32_16x16x32_bf16 v[56:59], v[164:167], v[194:197], v[56:59]
	v_mfma_f32_16x16x32_bf16 v[44:47], v[156:159], v[202:205], v[44:47]
	v_mfma_f32_16x16x32_bf16 v[40:43], v[164:167], v[202:205], v[40:43]
	v_mfma_f32_16x16x32_bf16 v[28:31], v[156:159], v[210:213], v[28:31]
	v_mfma_f32_16x16x32_bf16 v[24:27], v[164:167], v[210:213], v[24:27]
	v_mfma_f32_16x16x32_bf16 v[12:15], v[156:159], v[218:221], v[12:15]
	v_mfma_f32_16x16x32_bf16 v[8:11], v[164:167], v[218:221], v[8:11]
	s_setprio 0
	s_setprio 1
	v_mfma_f32_16x16x32_bf16 v[52:55], v[168:171], v[190:193], v[52:55]
	v_mfma_f32_16x16x32_bf16 v[48:51], v[176:179], v[190:193], v[48:51]
	v_mfma_f32_16x16x32_bf16 v[36:39], v[168:171], v[198:201], v[36:39]
	v_mfma_f32_16x16x32_bf16 v[32:35], v[176:179], v[198:201], v[32:35]
	v_mfma_f32_16x16x32_bf16 v[20:23], v[168:171], v[206:209], v[20:23]
	v_mfma_f32_16x16x32_bf16 v[16:19], v[176:179], v[206:209], v[16:19]
	v_mfma_f32_16x16x32_bf16 v[4:7], v[168:171], v[214:217], v[4:7]
	v_mfma_f32_16x16x32_bf16 v[0:3], v[176:179], v[214:217], v[0:3]
	v_mfma_f32_16x16x32_bf16 v[52:55], v[172:175], v[194:197], v[52:55]
	v_mfma_f32_16x16x32_bf16 v[48:51], v[186:189], v[194:197], v[48:51]
	v_mfma_f32_16x16x32_bf16 v[36:39], v[172:175], v[202:205], v[36:39]
	v_mfma_f32_16x16x32_bf16 v[32:35], v[186:189], v[202:205], v[32:35]
	v_mfma_f32_16x16x32_bf16 v[20:23], v[172:175], v[210:213], v[20:23]
	v_mfma_f32_16x16x32_bf16 v[16:19], v[186:189], v[210:213], v[16:19]
	v_mfma_f32_16x16x32_bf16 v[4:7], v[172:175], v[218:221], v[4:7]
	v_mfma_f32_16x16x32_bf16 v[0:3], v[186:189], v[218:221], v[0:3]
	s_setprio 0
	s_barrier
	s_add_i32 s58, s58, 2
	s_add_u32 s26, s26, 0x100
	s_addc_u32 s27, s27, 0
	s_add_u32 s56, s56, 0x100
	s_addc_u32 s57, s57, 0
	s_cmp_gt_u32 s58, 13

; DI unsigned cvtpk(float lo, float hi) { f32x2_t v = {lo, hi}; bf16x2_t b = __builtin_convertvector(v, bf16x2_t); return __builtin_bit_cast(unsigned, b); }
; DI float silu_f(float x) { return x * __builtin_amdgcn_rcpf(1.0f + __expf(-x)); }
;     DI void operator()(const f32x4 (&acc)[2][2][4][2], const Unit& u, int wr, int wc, int fr, int fq) const {
; #pragma unroll
;         for (int ai = 0; ai < 2; ++ai)
; #pragma unroll
;             for (int m = 0; m < 4; ++m) {
;                 const int row = u.pm * 256 + 128 * ai + 64 * wr + 16 * m + fr;
;                 const float* sp = SSQ + (size_t)row * 16;
;                 const f32x4 s0 = *(const f32x4*)sp, s1 = *(const f32x4*)(sp + 4), s2 = *(const f32x4*)(sp + 8), s3 = *(const f32x4*)(sp + 12);
;                 float ss = 0.f;
; #pragma unroll
;                 for (int i = 0; i < 4; ++i) ss += s0[i] + s1[i] + s2[i] + s3[i];
;                 const float rs = rsqrtf(ss * (1.0f / DM) + EPS);
;                 float a[8];
; #pragma unroll
;                 for (int n = 0; n < 2; ++n)
; #pragma unroll
;                     for (int t = 0; t < 4; ++t) a[4 * n + t] = silu_f(acc[ai][0][m][n][t] * rs) * (acc[ai][1][m][n][t] * rs);
;                 u32x4 w; w.x = cvtpk(a[0], a[1]); w.y = cvtpk(a[2], a[3]); w.z = cvtpk(a[4], a[5]); w.w = cvtpk(a[6], a[7]);
;                 __builtin_nontemporal_store(w, (u32x4*)(ACT + (size_t)row * DFF + u.pn * 128 + 32 * wc + 8 * fq));
;             }
.LBB0_863:
	v_lshl_add_u32 v148, s24, 8, v150
	v_ashrrev_i32_e32 v149, 31, v148
	v_lshlrev_b64 v[146:147], 6, v[148:149]
	v_pk_add_f32 v[186:187], v[230:231], v[234:235]
	v_pk_add_f32 v[188:189], v[232:233], v[236:237]
	v_pk_add_f32 v[186:187], v[238:239], v[186:187]
	v_pk_add_f32 v[188:189], v[240:241], v[188:189]
	v_pk_add_f32 v[186:187], v[242:243], v[186:187]
	v_pk_add_f32 v[188:189], v[244:245], v[188:189]
	v_add_f32_e32 v190, 0, v186
	v_add_f32_e32 v190, v187, v190
	v_add_f32_e32 v190, v188, v190
	v_add_f32_e32 v190, v189, v190
	v_fmamk_f32 v190, v190, 0x3a800000, v155
	v_mul_f32_e32 v191, 0x4b800000, v190
	v_cmp_gt_f32_e32 vcc, s47, v190
	s_nop 1
	v_cndmask_b32_e32 v190, v190, v191, vcc
	v_rsq_f32_e32 v190, v190
	s_nop 1
	v_mul_f32_e32 v191, 0x45800000, v190
	v_cndmask_b32_e32 v190, v190, v191, vcc
	ds_write_b32 v247, v190
	s_waitcnt lgkmcnt(0)
	s_barrier
	v_mov_b32_e32 v202, 0x20000
	v_lshl_add_u32 v202, v150, 2, v202
	ds_read_b32 v186, v202 offset:0
	ds_read_b32 v188, v202 offset:64
	ds_read_b32 v190, v202 offset:128
	ds_read_b32 v192, v202 offset:192
	ds_read_b32 v194, v202 offset:512
	ds_read_b32 v196, v202 offset:576
	ds_read_b32 v198, v202 offset:640
	ds_read_b32 v200, v202 offset:704
	s_lshl_b32 s24, s25, 7
	v_mov_b64_e32 v[146:147], s[52:53]
	s_ashr_i32 s25, s24, 31
	v_mad_i64_i32 v[172:173], s[26:27], v148, s48, v[146:147]
	s_lshl_b64 s[24:25], s[24:25], 1
	v_lshl_add_u64 v[172:173], v[172:173], 0, s[24:25]
	v_or_b32_e32 v174, 16, v148
	v_ashrrev_i32_e32 v175, 31, v174
	v_lshlrev_b64 v[176:177], 6, v[174:175]
	v_lshl_add_u64 v[156:157], v[172:173], 0, s[8:9]
	v_lshl_add_u64 v[156:157], v[156:157], 0, v[136:137]
	s_waitcnt lgkmcnt(7)
	v_pk_mul_f32 v[124:125], v[124:125], v[186:187] op_sel_hi:[1,0]
	v_pk_mul_f32 v[126:127], v[126:127], v[186:187] op_sel_hi:[1,0]
	v_pk_mul_f32 v[120:121], v[120:121], v[186:187] op_sel_hi:[1,0]
	v_pk_mul_f32 v[122:123], v[122:123], v[186:187] op_sel_hi:[1,0]
	v_pk_mul_f32 v[116:117], v[116:117], v[186:187] op_sel_hi:[1,0]
	v_pk_mul_f32 v[118:119], v[118:119], v[186:187] op_sel_hi:[1,0]
	v_pk_mul_f32 v[112:113], v[112:113], v[186:187] op_sel_hi:[1,0]
	v_pk_mul_f32 v[114:115], v[114:115], v[186:187] op_sel_hi:[1,0]
	v_mul_f32_e32 v149, 0xbfb8aa3b, v124
	v_mul_f32_e32 v160, 0xbfb8aa3b, v125
	v_mul_f32_e32 v161, 0xbfb8aa3b, v126
	v_mul_f32_e32 v162, 0xbfb8aa3b, v127
	v_mul_f32_e32 v163, 0xbfb8aa3b, v120
	v_mul_f32_e32 v164, 0xbfb8aa3b, v121
	v_mul_f32_e32 v165, 0xbfb8aa3b, v122
	v_mul_f32_e32 v166, 0xbfb8aa3b, v123
	v_exp_f32_e32 v149, v149
	v_exp_f32_e32 v160, v160
	v_exp_f32_e32 v161, v161
	v_exp_f32_e32 v162, v162
	v_exp_f32_e32 v163, v163
	v_exp_f32_e32 v164, v164
	v_exp_f32_e32 v165, v165
	v_exp_f32_e32 v166, v166
	v_add_f32_e32 v149, 1.0, v149
	v_add_f32_e32 v167, 1.0, v160
	v_add_f32_e32 v168, 1.0, v161
	v_add_f32_e32 v169, 1.0, v162
	v_add_f32_e32 v170, 1.0, v163
	v_add_f32_e32 v171, 1.0, v164
	v_add_f32_e32 v172, 1.0, v165
	v_add_f32_e32 v173, 1.0, v166
	v_rcp_f32_e32 v160, v149
	v_rcp_f32_e32 v161, v167
	v_rcp_f32_e32 v162, v168
	v_rcp_f32_e32 v163, v169
	v_rcp_f32_e32 v164, v170
	v_rcp_f32_e32 v165, v171
	v_rcp_f32_e32 v166, v172
	v_rcp_f32_e32 v167, v173
	v_pk_mul_f32 v[124:125], v[124:125], v[160:161]
	v_pk_mul_f32 v[126:127], v[126:127], v[162:163]
	v_pk_mul_f32 v[120:121], v[120:121], v[164:165]
	v_pk_mul_f32 v[122:123], v[122:123], v[166:167]
	v_pk_mul_f32 v[116:117], v[116:117], v[124:125]
	v_pk_mul_f32 v[118:119], v[118:119], v[126:127]
	v_pk_mul_f32 v[120:121], v[112:113], v[120:121]
	v_pk_mul_f32 v[122:123], v[114:115], v[122:123]
	v_cvt_pk_bf16_f32 v112, v116, v117
	v_cvt_pk_bf16_f32 v113, v118, v119
	v_cvt_pk_bf16_f32 v114, v120, v121
	v_cvt_pk_bf16_f32 v115, v122, v123
	global_store_dwordx4 v[156:157], v[112:115], off nt
	v_mad_i64_i32 v[158:159], s[26:27], v174, s48, v[146:147]
	v_or_b32_e32 v156, 32, v148
	v_lshl_add_u64 v[158:159], v[158:159], 0, s[24:25]
	v_ashrrev_i32_e32 v157, 31, v156
	v_lshlrev_b64 v[160:161], 6, v[156:157]
	v_lshl_add_u64 v[112:113], v[158:159], 0, s[8:9]
	v_lshl_add_u64 v[112:113], v[112:113], 0, v[136:137]
	s_waitcnt lgkmcnt(6)
	v_pk_mul_f32 v[108:109], v[108:109], v[188:189] op_sel_hi:[1,0]
	v_pk_mul_f32 v[110:111], v[110:111], v[188:189] op_sel_hi:[1,0]
	v_pk_mul_f32 v[104:105], v[104:105], v[188:189] op_sel_hi:[1,0]
	v_pk_mul_f32 v[106:107], v[106:107], v[188:189] op_sel_hi:[1,0]
	v_pk_mul_f32 v[100:101], v[100:101], v[188:189] op_sel_hi:[1,0]
	v_pk_mul_f32 v[102:103], v[102:103], v[188:189] op_sel_hi:[1,0]
	v_pk_mul_f32 v[96:97], v[96:97], v[188:189] op_sel_hi:[1,0]
	v_pk_mul_f32 v[98:99], v[98:99], v[188:189] op_sel_hi:[1,0]
	v_mul_f32_e32 v116, 0xbfb8aa3b, v108
	v_mul_f32_e32 v117, 0xbfb8aa3b, v109
	v_mul_f32_e32 v118, 0xbfb8aa3b, v110
	v_mul_f32_e32 v119, 0xbfb8aa3b, v111
	v_mul_f32_e32 v120, 0xbfb8aa3b, v104
	v_mul_f32_e32 v121, 0xbfb8aa3b, v105
	v_mul_f32_e32 v122, 0xbfb8aa3b, v106
	v_mul_f32_e32 v123, 0xbfb8aa3b, v107
	v_exp_f32_e32 v116, v116
	v_exp_f32_e32 v117, v117
	v_exp_f32_e32 v118, v118
	v_exp_f32_e32 v119, v119
	v_exp_f32_e32 v120, v120
	v_exp_f32_e32 v121, v121
	v_exp_f32_e32 v122, v122
	v_exp_f32_e32 v123, v123
	v_add_f32_e32 v116, 1.0, v116
	v_add_f32_e32 v117, 1.0, v117
	v_add_f32_e32 v118, 1.0, v118
	v_add_f32_e32 v119, 1.0, v119
	v_add_f32_e32 v120, 1.0, v120
	v_add_f32_e32 v121, 1.0, v121
	v_add_f32_e32 v122, 1.0, v122
	v_add_f32_e32 v123, 1.0, v123
	v_rcp_f32_e32 v116, v116
	v_rcp_f32_e32 v117, v117
	v_rcp_f32_e32 v118, v118
	v_rcp_f32_e32 v119, v119
	v_rcp_f32_e32 v120, v120
	v_rcp_f32_e32 v121, v121
	v_rcp_f32_e32 v122, v122
	v_rcp_f32_e32 v123, v123
	v_pk_mul_f32 v[108:109], v[108:109], v[116:117]
	v_pk_mul_f32 v[110:111], v[110:111], v[118:119]
	v_pk_mul_f32 v[104:105], v[104:105], v[120:121]
	v_pk_mul_f32 v[106:107], v[106:107], v[122:123]
	v_pk_mul_f32 v[100:101], v[100:101], v[108:109]
	v_pk_mul_f32 v[102:103], v[102:103], v[110:111]
	v_pk_mul_f32 v[104:105], v[96:97], v[104:105]
	v_pk_mul_f32 v[106:107], v[98:99], v[106:107]
	v_cvt_pk_bf16_f32 v96, v100, v101
	v_cvt_pk_bf16_f32 v97, v102, v103
	v_cvt_pk_bf16_f32 v98, v104, v105
	v_cvt_pk_bf16_f32 v99, v106, v107
	global_store_dwordx4 v[112:113], v[96:99], off nt
	v_mad_i64_i32 v[114:115], s[26:27], v156, s48, v[146:147]
	v_or_b32_e32 v112, 48, v148
	v_lshl_add_u64 v[114:115], v[114:115], 0, s[24:25]
	v_ashrrev_i32_e32 v113, 31, v112
	v_lshlrev_b64 v[116:117], 6, v[112:113]
	v_lshl_add_u64 v[96:97], v[114:115], 0, s[8:9]
	v_lshl_add_u64 v[96:97], v[96:97], 0, v[136:137]
	s_waitcnt lgkmcnt(5)
; DI unsigned cvtpk(float lo, float hi) { f32x2_t v = {lo, hi}; bf16x2_t b = __builtin_convertvector(v, bf16x2_t); return __builtin_bit_cast(unsigned, b); }
; DI float silu_f(float x) { return x * __builtin_amdgcn_rcpf(1.0f + __expf(-x)); }
;     DI void operator()(const f32x4 (&acc)[2][2][4][2], const Unit& u, int wr, int wc, int fr, int fq) const {
; #pragma unroll
;         for (int ai = 0; ai < 2; ++ai)
; #pragma unroll
;             for (int m = 0; m < 4; ++m) {
;                 const int row = u.pm * 256 + 128 * ai + 64 * wr + 16 * m + fr;
;                 const float* sp = SSQ + (size_t)row * 16;
;                 const f32x4 s0 = *(const f32x4*)sp, s1 = *(const f32x4*)(sp + 4), s2 = *(const f32x4*)(sp + 8), s3 = *(const f32x4*)(sp + 12);
;                 float ss = 0.f;
; #pragma unroll
;                 for (int i = 0; i < 4; ++i) ss += s0[i] + s1[i] + s2[i] + s3[i];
;                 const float rs = rsqrtf(ss * (1.0f / DM) + EPS);
;                 float a[8];
; #pragma unroll
;                 for (int n = 0; n < 2; ++n)
; #pragma unroll
;                     for (int t = 0; t < 4; ++t) a[4 * n + t] = silu_f(acc[ai][0][m][n][t] * rs) * (acc[ai][1][m][n][t] * rs);
;                 u32x4 w; w.x = cvtpk(a[0], a[1]); w.y = cvtpk(a[2], a[3]); w.z = cvtpk(a[4], a[5]); w.w = cvtpk(a[6], a[7]);
;                 __builtin_nontemporal_store(w, (u32x4*)(ACT + (size_t)row * DFF + u.pn * 128 + 32 * wc + 8 * fq));
;             }
	v_pk_mul_f32 v[92:93], v[92:93], v[190:191] op_sel_hi:[1,0]
	v_pk_mul_f32 v[94:95], v[94:95], v[190:191] op_sel_hi:[1,0]
	v_pk_mul_f32 v[88:89], v[88:89], v[190:191] op_sel_hi:[1,0]
	v_pk_mul_f32 v[90:91], v[90:91], v[190:191] op_sel_hi:[1,0]
	v_pk_mul_f32 v[84:85], v[84:85], v[190:191] op_sel_hi:[1,0]
	v_pk_mul_f32 v[86:87], v[86:87], v[190:191] op_sel_hi:[1,0]
	v_pk_mul_f32 v[80:81], v[80:81], v[190:191] op_sel_hi:[1,0]
	v_pk_mul_f32 v[82:83], v[82:83], v[190:191] op_sel_hi:[1,0]
	v_mul_f32_e32 v100, 0xbfb8aa3b, v92
	v_mul_f32_e32 v101, 0xbfb8aa3b, v93
	v_mul_f32_e32 v102, 0xbfb8aa3b, v94
	v_mul_f32_e32 v103, 0xbfb8aa3b, v95
	v_mul_f32_e32 v104, 0xbfb8aa3b, v88
	v_mul_f32_e32 v105, 0xbfb8aa3b, v89
	v_mul_f32_e32 v106, 0xbfb8aa3b, v90
	v_mul_f32_e32 v107, 0xbfb8aa3b, v91
	v_exp_f32_e32 v100, v100
	v_exp_f32_e32 v101, v101
	v_exp_f32_e32 v102, v102
	v_exp_f32_e32 v103, v103
	v_exp_f32_e32 v104, v104
	v_exp_f32_e32 v105, v105
	v_exp_f32_e32 v106, v106
	v_exp_f32_e32 v107, v107
	v_add_f32_e32 v100, 1.0, v100
	v_add_f32_e32 v101, 1.0, v101
	v_add_f32_e32 v102, 1.0, v102
	v_add_f32_e32 v103, 1.0, v103
	v_add_f32_e32 v104, 1.0, v104
	v_add_f32_e32 v105, 1.0, v105
	v_add_f32_e32 v106, 1.0, v106
	v_add_f32_e32 v107, 1.0, v107
	v_rcp_f32_e32 v100, v100
	v_rcp_f32_e32 v101, v101
	v_rcp_f32_e32 v102, v102
	v_rcp_f32_e32 v103, v103
	v_rcp_f32_e32 v104, v104
	v_rcp_f32_e32 v105, v105
	v_rcp_f32_e32 v106, v106
	v_rcp_f32_e32 v107, v107
	v_pk_mul_f32 v[92:93], v[92:93], v[100:101]
	v_pk_mul_f32 v[94:95], v[94:95], v[102:103]
	v_pk_mul_f32 v[88:89], v[88:89], v[104:105]
	v_pk_mul_f32 v[90:91], v[90:91], v[106:107]
	v_pk_mul_f32 v[84:85], v[84:85], v[92:93]
	v_pk_mul_f32 v[86:87], v[86:87], v[94:95]
	v_pk_mul_f32 v[88:89], v[80:81], v[88:89]
	v_pk_mul_f32 v[90:91], v[82:83], v[90:91]
	v_cvt_pk_bf16_f32 v80, v84, v85
	v_cvt_pk_bf16_f32 v81, v86, v87
	v_cvt_pk_bf16_f32 v82, v88, v89
	v_cvt_pk_bf16_f32 v83, v90, v91
	global_store_dwordx4 v[96:97], v[80:83], off nt
	v_mad_i64_i32 v[98:99], s[26:27], v112, s48, v[146:147]
	v_add_u32_e32 v96, 0x80, v148
	v_lshl_add_u64 v[98:99], v[98:99], 0, s[24:25]
	v_ashrrev_i32_e32 v97, 31, v96
	v_lshlrev_b64 v[100:101], 6, v[96:97]
	v_lshl_add_u64 v[80:81], v[98:99], 0, s[8:9]
	v_lshl_add_u64 v[80:81], v[80:81], 0, v[136:137]
	s_waitcnt lgkmcnt(4)
	v_pk_mul_f32 v[76:77], v[76:77], v[192:193] op_sel_hi:[1,0]
	v_pk_mul_f32 v[78:79], v[78:79], v[192:193] op_sel_hi:[1,0]
	v_pk_mul_f32 v[72:73], v[72:73], v[192:193] op_sel_hi:[1,0]
	v_pk_mul_f32 v[74:75], v[74:75], v[192:193] op_sel_hi:[1,0]
	v_pk_mul_f32 v[68:69], v[68:69], v[192:193] op_sel_hi:[1,0]
	v_pk_mul_f32 v[70:71], v[70:71], v[192:193] op_sel_hi:[1,0]
	v_pk_mul_f32 v[64:65], v[64:65], v[192:193] op_sel_hi:[1,0]
	v_pk_mul_f32 v[66:67], v[66:67], v[192:193] op_sel_hi:[1,0]
	v_mul_f32_e32 v84, 0xbfb8aa3b, v76
	v_mul_f32_e32 v85, 0xbfb8aa3b, v77
	v_mul_f32_e32 v86, 0xbfb8aa3b, v78
	v_mul_f32_e32 v87, 0xbfb8aa3b, v79
	v_mul_f32_e32 v88, 0xbfb8aa3b, v72
	v_mul_f32_e32 v89, 0xbfb8aa3b, v73
	v_mul_f32_e32 v90, 0xbfb8aa3b, v74
	v_mul_f32_e32 v91, 0xbfb8aa3b, v75
	v_exp_f32_e32 v84, v84
	v_exp_f32_e32 v85, v85
	v_exp_f32_e32 v86, v86
	v_exp_f32_e32 v87, v87
	v_exp_f32_e32 v88, v88
	v_exp_f32_e32 v89, v89
	v_exp_f32_e32 v90, v90
	v_exp_f32_e32 v91, v91
	v_add_f32_e32 v84, 1.0, v84
	v_add_f32_e32 v85, 1.0, v85
	v_add_f32_e32 v86, 1.0, v86
	v_add_f32_e32 v87, 1.0, v87
	v_add_f32_e32 v88, 1.0, v88
	v_add_f32_e32 v89, 1.0, v89
	v_add_f32_e32 v90, 1.0, v90
	v_add_f32_e32 v91, 1.0, v91
	v_rcp_f32_e32 v84, v84
	v_rcp_f32_e32 v85, v85
	v_rcp_f32_e32 v86, v86
	v_rcp_f32_e32 v87, v87
	v_rcp_f32_e32 v88, v88
	v_rcp_f32_e32 v89, v89
	v_rcp_f32_e32 v90, v90
	v_rcp_f32_e32 v91, v91
	v_pk_mul_f32 v[76:77], v[76:77], v[84:85]
	v_pk_mul_f32 v[78:79], v[78:79], v[86:87]
	v_pk_mul_f32 v[72:73], v[72:73], v[88:89]
	v_pk_mul_f32 v[74:75], v[74:75], v[90:91]
	v_pk_mul_f32 v[68:69], v[68:69], v[76:77]
	v_pk_mul_f32 v[70:71], v[70:71], v[78:79]
	v_pk_mul_f32 v[72:73], v[64:65], v[72:73]
	v_pk_mul_f32 v[74:75], v[66:67], v[74:75]
	v_cvt_pk_bf16_f32 v64, v68, v69
	v_cvt_pk_bf16_f32 v65, v70, v71
	v_cvt_pk_bf16_f32 v66, v72, v73
	v_cvt_pk_bf16_f32 v67, v74, v75
	global_store_dwordx4 v[80:81], v[64:67], off nt
	v_mad_i64_i32 v[82:83], s[26:27], v96, s48, v[146:147]
	v_add_u32_e32 v80, 0x90, v148
	v_lshl_add_u64 v[82:83], v[82:83], 0, s[24:25]
	v_ashrrev_i32_e32 v81, 31, v80
	v_lshlrev_b64 v[84:85], 6, v[80:81]
	v_lshl_add_u64 v[64:65], v[82:83], 0, s[8:9]
	v_lshl_add_u64 v[64:65], v[64:65], 0, v[136:137]
	s_waitcnt lgkmcnt(3)
; DI unsigned cvtpk(float lo, float hi) { f32x2_t v = {lo, hi}; bf16x2_t b = __builtin_convertvector(v, bf16x2_t); return __builtin_bit_cast(unsigned, b); }
; DI float silu_f(float x) { return x * __builtin_amdgcn_rcpf(1.0f + __expf(-x)); }
;     DI void operator()(const f32x4 (&acc)[2][2][4][2], const Unit& u, int wr, int wc, int fr, int fq) const {
; #pragma unroll
;         for (int ai = 0; ai < 2; ++ai)
; #pragma unroll
;             for (int m = 0; m < 4; ++m) {
;                 const int row = u.pm * 256 + 128 * ai + 64 * wr + 16 * m + fr;
;                 const float* sp = SSQ + (size_t)row * 16;
;                 const f32x4 s0 = *(const f32x4*)sp, s1 = *(const f32x4*)(sp + 4), s2 = *(const f32x4*)(sp + 8), s3 = *(const f32x4*)(sp + 12);
;                 float ss = 0.f;
; #pragma unroll
;                 for (int i = 0; i < 4; ++i) ss += s0[i] + s1[i] + s2[i] + s3[i];
;                 const float rs = rsqrtf(ss * (1.0f / DM) + EPS);
;                 float a[8];
; #pragma unroll
;                 for (int n = 0; n < 2; ++n)
; #pragma unroll
;                     for (int t = 0; t < 4; ++t) a[4 * n + t] = silu_f(acc[ai][0][m][n][t] * rs) * (acc[ai][1][m][n][t] * rs);
;                 u32x4 w; w.x = cvtpk(a[0], a[1]); w.y = cvtpk(a[2], a[3]); w.z = cvtpk(a[4], a[5]); w.w = cvtpk(a[6], a[7]);
;                 __builtin_nontemporal_store(w, (u32x4*)(ACT + (size_t)row * DFF + u.pn * 128 + 32 * wc + 8 * fq));
;             }
	v_pk_mul_f32 v[60:61], v[60:61], v[194:195] op_sel_hi:[1,0]
	v_pk_mul_f32 v[62:63], v[62:63], v[194:195] op_sel_hi:[1,0]
	v_pk_mul_f32 v[56:57], v[56:57], v[194:195] op_sel_hi:[1,0]
	v_pk_mul_f32 v[58:59], v[58:59], v[194:195] op_sel_hi:[1,0]
	v_pk_mul_f32 v[52:53], v[52:53], v[194:195] op_sel_hi:[1,0]
	v_pk_mul_f32 v[54:55], v[54:55], v[194:195] op_sel_hi:[1,0]
	v_pk_mul_f32 v[48:49], v[48:49], v[194:195] op_sel_hi:[1,0]
	v_pk_mul_f32 v[50:51], v[50:51], v[194:195] op_sel_hi:[1,0]
	v_mul_f32_e32 v68, 0xbfb8aa3b, v60
	v_mul_f32_e32 v69, 0xbfb8aa3b, v61
	v_mul_f32_e32 v70, 0xbfb8aa3b, v62
	v_mul_f32_e32 v71, 0xbfb8aa3b, v63
	v_mul_f32_e32 v72, 0xbfb8aa3b, v56
	v_mul_f32_e32 v73, 0xbfb8aa3b, v57
	v_mul_f32_e32 v74, 0xbfb8aa3b, v58
	v_mul_f32_e32 v75, 0xbfb8aa3b, v59
	v_exp_f32_e32 v68, v68
	v_exp_f32_e32 v69, v69
	v_exp_f32_e32 v70, v70
	v_exp_f32_e32 v71, v71
	v_exp_f32_e32 v72, v72
	v_exp_f32_e32 v73, v73
	v_exp_f32_e32 v74, v74
	v_exp_f32_e32 v75, v75
	v_add_f32_e32 v68, 1.0, v68
	v_add_f32_e32 v69, 1.0, v69
	v_add_f32_e32 v70, 1.0, v70
	v_add_f32_e32 v71, 1.0, v71
	v_add_f32_e32 v72, 1.0, v72
	v_add_f32_e32 v73, 1.0, v73
	v_add_f32_e32 v74, 1.0, v74
	v_add_f32_e32 v75, 1.0, v75
	v_rcp_f32_e32 v68, v68
	v_rcp_f32_e32 v69, v69
	v_rcp_f32_e32 v70, v70
	v_rcp_f32_e32 v71, v71
	v_rcp_f32_e32 v72, v72
	v_rcp_f32_e32 v73, v73
	v_rcp_f32_e32 v74, v74
	v_rcp_f32_e32 v75, v75
	v_pk_mul_f32 v[60:61], v[60:61], v[68:69]
	v_pk_mul_f32 v[62:63], v[62:63], v[70:71]
	v_pk_mul_f32 v[56:57], v[56:57], v[72:73]
	v_pk_mul_f32 v[58:59], v[58:59], v[74:75]
	v_pk_mul_f32 v[52:53], v[52:53], v[60:61]
	v_pk_mul_f32 v[54:55], v[54:55], v[62:63]
	v_pk_mul_f32 v[56:57], v[48:49], v[56:57]
	v_pk_mul_f32 v[58:59], v[50:51], v[58:59]
	v_cvt_pk_bf16_f32 v48, v52, v53
	v_cvt_pk_bf16_f32 v49, v54, v55
	v_cvt_pk_bf16_f32 v50, v56, v57
	v_cvt_pk_bf16_f32 v51, v58, v59
	global_store_dwordx4 v[64:65], v[48:51], off nt
	v_mad_i64_i32 v[66:67], s[26:27], v80, s48, v[146:147]
	v_add_u32_e32 v64, 0xa0, v148
	v_lshl_add_u64 v[66:67], v[66:67], 0, s[24:25]
	v_ashrrev_i32_e32 v65, 31, v64
	v_lshlrev_b64 v[68:69], 6, v[64:65]
	v_lshl_add_u64 v[48:49], v[66:67], 0, s[8:9]
	v_lshl_add_u64 v[48:49], v[48:49], 0, v[136:137]
	s_waitcnt lgkmcnt(2)
	v_pk_mul_f32 v[44:45], v[44:45], v[196:197] op_sel_hi:[1,0]
	v_pk_mul_f32 v[46:47], v[46:47], v[196:197] op_sel_hi:[1,0]
	v_pk_mul_f32 v[40:41], v[40:41], v[196:197] op_sel_hi:[1,0]
	v_pk_mul_f32 v[42:43], v[42:43], v[196:197] op_sel_hi:[1,0]
	v_pk_mul_f32 v[36:37], v[36:37], v[196:197] op_sel_hi:[1,0]
	v_pk_mul_f32 v[38:39], v[38:39], v[196:197] op_sel_hi:[1,0]
	v_pk_mul_f32 v[32:33], v[32:33], v[196:197] op_sel_hi:[1,0]
	v_pk_mul_f32 v[34:35], v[34:35], v[196:197] op_sel_hi:[1,0]
	v_mul_f32_e32 v52, 0xbfb8aa3b, v44
	v_mul_f32_e32 v53, 0xbfb8aa3b, v45
	v_mul_f32_e32 v54, 0xbfb8aa3b, v46
	v_mul_f32_e32 v55, 0xbfb8aa3b, v47
	v_mul_f32_e32 v56, 0xbfb8aa3b, v40
	v_mul_f32_e32 v57, 0xbfb8aa3b, v41
	v_mul_f32_e32 v58, 0xbfb8aa3b, v42
	v_mul_f32_e32 v59, 0xbfb8aa3b, v43
	v_exp_f32_e32 v52, v52
	v_exp_f32_e32 v53, v53
	v_exp_f32_e32 v54, v54
	v_exp_f32_e32 v55, v55
	v_exp_f32_e32 v56, v56
	v_exp_f32_e32 v57, v57
	v_exp_f32_e32 v58, v58
	v_exp_f32_e32 v59, v59
	v_add_f32_e32 v52, 1.0, v52
	v_add_f32_e32 v53, 1.0, v53
	v_add_f32_e32 v54, 1.0, v54
	v_add_f32_e32 v55, 1.0, v55
	v_add_f32_e32 v56, 1.0, v56
	v_add_f32_e32 v57, 1.0, v57
	v_add_f32_e32 v58, 1.0, v58
	v_add_f32_e32 v59, 1.0, v59
	v_rcp_f32_e32 v52, v52
	v_rcp_f32_e32 v53, v53
	v_rcp_f32_e32 v54, v54
	v_rcp_f32_e32 v55, v55
	v_rcp_f32_e32 v56, v56
	v_rcp_f32_e32 v57, v57
	v_rcp_f32_e32 v58, v58
	v_rcp_f32_e32 v59, v59
	v_pk_mul_f32 v[44:45], v[44:45], v[52:53]
	v_pk_mul_f32 v[46:47], v[46:47], v[54:55]
	v_pk_mul_f32 v[40:41], v[40:41], v[56:57]
	v_pk_mul_f32 v[42:43], v[42:43], v[58:59]
	v_pk_mul_f32 v[36:37], v[36:37], v[44:45]
	v_pk_mul_f32 v[38:39], v[38:39], v[46:47]
	v_pk_mul_f32 v[40:41], v[32:33], v[40:41]
	v_pk_mul_f32 v[42:43], v[34:35], v[42:43]
	v_cvt_pk_bf16_f32 v32, v36, v37
	v_cvt_pk_bf16_f32 v33, v38, v39
	v_cvt_pk_bf16_f32 v34, v40, v41
	v_cvt_pk_bf16_f32 v35, v42, v43
	global_store_dwordx4 v[48:49], v[32:35], off nt
	v_mad_i64_i32 v[50:51], s[26:27], v64, s48, v[146:147]
	v_add_u32_e32 v48, 0xb0, v148
	v_lshl_add_u64 v[50:51], v[50:51], 0, s[24:25]
	v_ashrrev_i32_e32 v49, 31, v48
	v_lshlrev_b64 v[52:53], 6, v[48:49]
	v_lshl_add_u64 v[32:33], v[50:51], 0, s[8:9]
	v_lshl_add_u64 v[32:33], v[32:33], 0, v[136:137]
	s_waitcnt lgkmcnt(1)
; DI unsigned cvtpk(float lo, float hi) { f32x2_t v = {lo, hi}; bf16x2_t b = __builtin_convertvector(v, bf16x2_t); return __builtin_bit_cast(unsigned, b); }
; DI float silu_f(float x) { return x * __builtin_amdgcn_rcpf(1.0f + __expf(-x)); }
;     DI void operator()(const f32x4 (&acc)[2][2][4][2], const Unit& u, int wr, int wc, int fr, int fq) const {
;     ...
;                 const int row = u.pm * 256 + 128 * ai + 64 * wr + 16 * m + fr;
;                 const float* sp = SSQ + (size_t)row * 16;
;                 const f32x4 s0 = *(const f32x4*)sp, s1 = *(const f32x4*)(sp + 4), s2 = *(const f32x4*)(sp + 8), s3 = *(const f32x4*)(sp + 12);
;                 float ss = 0.f;
; #pragma unroll
;                 for (int i = 0; i < 4; ++i) ss += s0[i] + s1[i] + s2[i] + s3[i];
;                 const float rs = rsqrtf(ss * (1.0f / DM) + EPS);
;                 float a[8];
; #pragma unroll
;                 for (int n = 0; n < 2; ++n)
; #pragma unroll
;                     for (int t = 0; t < 4; ++t) a[4 * n + t] = silu_f(acc[ai][0][m][n][t] * rs) * (acc[ai][1][m][n][t] * rs);
;                 u32x4 w; w.x = cvtpk(a[0], a[1]); w.y = cvtpk(a[2], a[3]); w.z = cvtpk(a[4], a[5]); w.w = cvtpk(a[6], a[7]);
;                 __builtin_nontemporal_store(w, (u32x4*)(ACT + (size_t)row * DFF + u.pn * 128 + 32 * wc + 8 * fq));
	v_pk_mul_f32 v[28:29], v[28:29], v[198:199] op_sel_hi:[1,0]
	v_pk_mul_f32 v[30:31], v[30:31], v[198:199] op_sel_hi:[1,0]
	v_pk_mul_f32 v[24:25], v[24:25], v[198:199] op_sel_hi:[1,0]
	v_pk_mul_f32 v[26:27], v[26:27], v[198:199] op_sel_hi:[1,0]
	v_pk_mul_f32 v[20:21], v[20:21], v[198:199] op_sel_hi:[1,0]
	v_pk_mul_f32 v[22:23], v[22:23], v[198:199] op_sel_hi:[1,0]
	v_pk_mul_f32 v[16:17], v[16:17], v[198:199] op_sel_hi:[1,0]
	v_pk_mul_f32 v[18:19], v[18:19], v[198:199] op_sel_hi:[1,0]
	v_mul_f32_e32 v36, 0xbfb8aa3b, v28
	v_mul_f32_e32 v37, 0xbfb8aa3b, v29
	v_mul_f32_e32 v38, 0xbfb8aa3b, v30
	v_mul_f32_e32 v39, 0xbfb8aa3b, v31
	v_mul_f32_e32 v40, 0xbfb8aa3b, v24
	v_mul_f32_e32 v41, 0xbfb8aa3b, v25
	v_mul_f32_e32 v42, 0xbfb8aa3b, v26
	v_mul_f32_e32 v43, 0xbfb8aa3b, v27
	v_exp_f32_e32 v36, v36
	v_exp_f32_e32 v37, v37
	v_exp_f32_e32 v38, v38
	v_exp_f32_e32 v39, v39
	v_exp_f32_e32 v40, v40
	v_exp_f32_e32 v41, v41
	v_exp_f32_e32 v42, v42
	v_exp_f32_e32 v43, v43
	v_add_f32_e32 v36, 1.0, v36
	v_add_f32_e32 v37, 1.0, v37
	v_add_f32_e32 v38, 1.0, v38
	v_add_f32_e32 v39, 1.0, v39
	v_add_f32_e32 v40, 1.0, v40
	v_add_f32_e32 v41, 1.0, v41
	v_add_f32_e32 v42, 1.0, v42
	v_add_f32_e32 v43, 1.0, v43
	v_rcp_f32_e32 v36, v36
	v_rcp_f32_e32 v37, v37
	v_rcp_f32_e32 v38, v38
	v_rcp_f32_e32 v39, v39
	v_rcp_f32_e32 v40, v40
	v_rcp_f32_e32 v41, v41
	v_rcp_f32_e32 v42, v42
	v_rcp_f32_e32 v43, v43
	v_pk_mul_f32 v[28:29], v[28:29], v[36:37]
	v_pk_mul_f32 v[30:31], v[30:31], v[38:39]
	v_pk_mul_f32 v[24:25], v[24:25], v[40:41]
	v_pk_mul_f32 v[26:27], v[26:27], v[42:43]
	v_pk_mul_f32 v[20:21], v[20:21], v[28:29]
	v_pk_mul_f32 v[22:23], v[22:23], v[30:31]
	v_pk_mul_f32 v[24:25], v[16:17], v[24:25]
	v_pk_mul_f32 v[26:27], v[18:19], v[26:27]
	v_cvt_pk_bf16_f32 v16, v20, v21
	v_cvt_pk_bf16_f32 v17, v22, v23
	v_cvt_pk_bf16_f32 v18, v24, v25
	v_cvt_pk_bf16_f32 v19, v26, v27
	global_store_dwordx4 v[32:33], v[16:19], off nt
	s_andn2_b64 vcc, exec, s[6:7]
	v_mad_i64_i32 v[32:33], s[26:27], v48, s48, v[146:147]
	v_lshl_add_u64 v[16:17], v[32:33], 0, s[24:25]
	v_lshl_add_u64 v[16:17], v[16:17], 0, s[8:9]
	v_lshl_add_u64 v[16:17], v[16:17], 0, v[136:137]
	s_waitcnt lgkmcnt(0)
	v_pk_mul_f32 v[12:13], v[12:13], v[200:201] op_sel_hi:[1,0]
	v_pk_mul_f32 v[14:15], v[14:15], v[200:201] op_sel_hi:[1,0]
	v_pk_mul_f32 v[8:9], v[8:9], v[200:201] op_sel_hi:[1,0]
	v_pk_mul_f32 v[10:11], v[10:11], v[200:201] op_sel_hi:[1,0]
	v_pk_mul_f32 v[4:5], v[4:5], v[200:201] op_sel_hi:[1,0]
	v_pk_mul_f32 v[6:7], v[6:7], v[200:201] op_sel_hi:[1,0]
	v_pk_mul_f32 v[0:1], v[0:1], v[200:201] op_sel_hi:[1,0]
	v_pk_mul_f32 v[2:3], v[2:3], v[200:201] op_sel_hi:[1,0]
	v_mul_f32_e32 v18, 0xbfb8aa3b, v12
	v_mul_f32_e32 v19, 0xbfb8aa3b, v13
	v_mul_f32_e32 v20, 0xbfb8aa3b, v14
	v_mul_f32_e32 v21, 0xbfb8aa3b, v15
	v_mul_f32_e32 v22, 0xbfb8aa3b, v8
	v_mul_f32_e32 v23, 0xbfb8aa3b, v9
	v_mul_f32_e32 v24, 0xbfb8aa3b, v10
	v_mul_f32_e32 v25, 0xbfb8aa3b, v11
	v_exp_f32_e32 v18, v18
	v_exp_f32_e32 v19, v19
	v_exp_f32_e32 v20, v20
	v_exp_f32_e32 v21, v21
	v_exp_f32_e32 v22, v22
	v_exp_f32_e32 v23, v23
	v_exp_f32_e32 v24, v24
	v_exp_f32_e32 v25, v25
	v_add_f32_e32 v18, 1.0, v18
	v_add_f32_e32 v19, 1.0, v19
	v_add_f32_e32 v20, 1.0, v20
	v_add_f32_e32 v21, 1.0, v21
	v_add_f32_e32 v22, 1.0, v22
	v_add_f32_e32 v23, 1.0, v23
	v_add_f32_e32 v24, 1.0, v24
	v_add_f32_e32 v25, 1.0, v25
	v_rcp_f32_e32 v18, v18
	v_rcp_f32_e32 v19, v19
	v_rcp_f32_e32 v20, v20
	v_rcp_f32_e32 v21, v21
	v_rcp_f32_e32 v22, v22
	v_rcp_f32_e32 v23, v23
	v_rcp_f32_e32 v24, v24
	v_rcp_f32_e32 v25, v25
	v_pk_mul_f32 v[12:13], v[12:13], v[18:19]
	v_pk_mul_f32 v[14:15], v[14:15], v[20:21]
	v_pk_mul_f32 v[8:9], v[8:9], v[22:23]
	v_pk_mul_f32 v[10:11], v[10:11], v[24:25]
	v_pk_mul_f32 v[4:5], v[4:5], v[12:13]
	v_pk_mul_f32 v[6:7], v[6:7], v[14:15]
	v_pk_mul_f32 v[8:9], v[0:1], v[8:9]
	v_pk_mul_f32 v[10:11], v[2:3], v[10:11]
	v_cvt_pk_bf16_f32 v0, v4, v5
	v_cvt_pk_bf16_f32 v1, v6, v7
	v_cvt_pk_bf16_f32 v2, v8, v9
	v_cvt_pk_bf16_f32 v3, v10, v11
	s_mov_b64 s[6:7], -1
	global_store_dwordx4 v[16:17], v[0:3], off nt
	s_cbranch_vccnz .LBB0_856
	s_andn2_b64 vcc, exec, s[10:11]
	s_cbranch_vccnz .LBB0_855
	s_barrier
	s_branch .LBB0_855
